# scan workgroups re-chosen: odd streams x odd query-block slots (64) + 4 for S5, so the largest first units never start late
# speedup vs baseline: 1.0188x; 1.0002x over previous
; __global__ void __launch_bounds__(NWAVES * 64, 2) hymba_fwd(Args args) {
;     ...
;             unsigned* scnt = (unsigned*)(ws + WS_SCNT) + layer * 64;
;             { unsigned ndone = 0;
;               if (wave < 2) { for (int t2 = wave * G + vcu; t2 < 512; t2 += 2 * G) { hgrn_scan(pa, t2, lane); ++ndone; } }
;               else if (wave == 2) { for (int t2 = vcu; t2 < 32; t2 += G) { s5_scan(pa, layer, t2, lane); ++ndone; } }
;               if (ndone) { asm volatile("s_waitcnt vmcnt(0)" ::: "memory"); if (lane == 0) (void)__hip_atomic_fetch_add(scnt, ndone, __ATOMIC_RELAXED, __HIP_MEMORY_SCOPE_AGENT); } }
.LBB0_554:
	s_or_b64 exec, exec, s[0:1]
	s_waitcnt lgkmcnt(0)
	s_barrier
	s_mov_b32 s37, 0
	v_readlane_b32 s12, v253, 18
	v_readlane_b32 s0, v252, 0
	s_lshr_b32 s1, s0, 4
	s_and_b32 s3, s0, 0x11
	s_cmp_eq_u32 s3, 0x11
	s_cbranch_scc1 .Lmy_sc_hsel
	s_and_b32 s3, s0, 0x3f
	s_cmp_eq_u32 s3, 14
	s_cbranch_scc0 .LBB0_569
	s_lshr_b32 s3, s1, 2
	s_lshl_b32 s3, s3, 3
	s_add_i32 s3, s3, s36
	v_readlane_b32 s0, v254, 44
	s_lshl_b32 s38, s0, 12
	v_readlane_b32 s0, v252, 18
	v_writelane_b32 v255, s74, 7
	v_lshlrev_b32_e32 v220, 2, v140
	v_readlane_b32 s1, v252, 19
	v_writelane_b32 v255, s75, 8
	v_lshlrev_b32_e32 v2, 2, v140
	v_lshl_add_u64 v[0:1], s[0:1], 0, v[220:221]
	s_mov_b32 s39, s3
	s_branch .LBB0_557
.Lmy_sc_hsel:
	s_lshr_b32 s1, s1, 1
	s_lshl_b32 s1, s1, 3
	s_bfe_u32 s3, s0, 0x30001
	s_or_b32 s1, s1, s3
	s_lshl_b32 s1, s1, 3
	s_add_i32 s2, s1, s36
	v_and_b32_e32 v6, 3, v141
	v_lshlrev_b32_e32 v220, 2, v140
	s_branch .LBB0_566
